# P0 weight conversion with gain folding: 8 serialized (row load, gain load, wait) round trips per iteration batched into one
# speedup vs baseline: 1.0449x; 1.0041x over previous
.LBB0_107:
	v_ashrrev_i32_e32 v0, 6, v38
	v_mul_hi_i32 v1, v0, s11
	v_lshrrev_b32_e32 v2, 31, v1
	v_ashrrev_i32_e32 v1, 4, v1
	v_add_u32_e32 v1, v1, v2
	v_mul_lo_u32 v2, v1, s12
	v_sub_u32_e32 v0, v0, v2
	v_and_b32_e32 v2, 56, v37
	v_lshlrev_b32_e32 v39, 5, v0
	v_lshl_or_b32 v32, v1, 6, v2
	v_lshlrev_b32_e32 v2, 6, v0
	v_lshrrev_b32_e32 v4, 3, v38
	v_and_b32_e32 v1, 0xffffff00, v39
	v_and_b32_e32 v2, 0xc0, v2
	v_lshlrev_b32_e32 v0, 3, v0
	v_and_b32_e32 v4, 4, v4
	v_and_b32_e32 v0, 32, v0
	v_and_b32_e32 v3, 24, v38
	v_or3_b32 v1, v1, v4, v2
	v_or3_b32 v0, v1, v0, v3
	v_readlane_b32 s36, v246, 22
	v_ashrrev_i32_e32 v1, 31, v0
	v_readlane_b32 s38, v246, 24
	v_readlane_b32 s39, v246, 25
	v_readlane_b32 s37, v246, 23
	v_ashrrev_i32_e32 v33, 31, v32
	v_lshl_add_u64 v[28:29], v[0:1], 2, s[38:39]
	v_mad_i64_i32 v[0:1], s[18:19], v32, s13, v[28:29]
	global_load_dwordx4 v[0:3], v[0:1], off nt
	v_lshl_add_u64 v[34:35], v[32:33], 2, s[36:37]
	v_readlane_b32 s40, v246, 26
	v_readlane_b32 s41, v246, 27
	v_readlane_b32 s42, v246, 28
	v_readlane_b32 s43, v246, 29
	v_readlane_b32 s44, v246, 30
	v_readlane_b32 s45, v246, 31
	v_readlane_b32 s46, v246, 32
	v_readlane_b32 s47, v246, 33
	v_readlane_b32 s48, v246, 34
	v_readlane_b32 s49, v246, 35
	v_readlane_b32 s50, v246, 36
	v_readlane_b32 s51, v246, 37
	v_or_b32_e32 v4, 1, v32
	v_mad_i64_i32 v[4:5], s[18:19], v4, s13, v[28:29]
	global_load_dwordx4 v[4:7], v[4:5], off nt
	v_or_b32_e32 v8, 2, v32
	v_mad_i64_i32 v[8:9], s[18:19], v8, s13, v[28:29]
	global_load_dwordx4 v[8:11], v[8:9], off nt
	v_or_b32_e32 v12, 3, v32
	v_mad_i64_i32 v[12:13], s[18:19], v12, s13, v[28:29]
	global_load_dwordx4 v[12:15], v[12:13], off nt
	v_or_b32_e32 v16, 4, v32
	v_mad_i64_i32 v[16:17], s[18:19], v16, s13, v[28:29]
	global_load_dwordx4 v[16:19], v[16:17], off nt
	s_waitcnt lgkmcnt(0)
	v_or_b32_e32 v20, 5, v32
	s_waitcnt lgkmcnt(0)
	v_mad_i64_i32 v[20:21], s[18:19], v20, s13, v[28:29]
	global_load_dwordx4 v[20:23], v[20:21], off nt
	v_or_b32_e32 v24, 6, v32
	v_mad_i64_i32 v[24:25], s[18:19], v24, s13, v[28:29]
	global_load_dwordx4 v[24:27], v[24:25], off nt
	v_or_b32_e32 v30, 7, v32
	v_mad_i64_i32 v[28:29], s[18:19], v30, s13, v[28:29]
	global_load_dwordx4 v[28:31], v[28:29], off nt
	s_and_b64 vcc, exec, s[0:1]
	s_cbranch_vccnz .LBB0_106
	global_load_dwordx4 v[48:51], v[34:35], off
	global_load_dwordx4 v[52:55], v[34:35], off offset:16
	s_waitcnt vmcnt(0)
	v_mul_f32_e32 v0, v0, v48
	v_mul_f32_e32 v1, v1, v48
	v_mul_f32_e32 v2, v2, v48
	v_mul_f32_e32 v3, v3, v48
	v_mul_f32_e32 v4, v4, v49
	v_mul_f32_e32 v5, v5, v49
	v_mul_f32_e32 v6, v6, v49
	v_mul_f32_e32 v7, v7, v49
	v_mul_f32_e32 v8, v8, v50
	v_mul_f32_e32 v9, v9, v50
	v_mul_f32_e32 v10, v10, v50
	v_mul_f32_e32 v11, v11, v50
	v_mul_f32_e32 v12, v12, v51
	v_mul_f32_e32 v13, v13, v51
	v_mul_f32_e32 v14, v14, v51
	v_mul_f32_e32 v15, v15, v51
	v_mul_f32_e32 v16, v16, v52
	v_mul_f32_e32 v17, v17, v52
	v_mul_f32_e32 v18, v18, v52
	v_mul_f32_e32 v19, v19, v52
	v_mul_f32_e32 v20, v20, v53
	v_mul_f32_e32 v21, v21, v53
	v_mul_f32_e32 v22, v22, v53
	v_mul_f32_e32 v23, v23, v53
	v_mul_f32_e32 v24, v24, v54
	v_mul_f32_e32 v25, v25, v54
	v_mul_f32_e32 v26, v26, v54
	v_mul_f32_e32 v27, v27, v54
	v_mul_f32_e32 v28, v28, v55
	v_mul_f32_e32 v29, v29, v55
	v_mul_f32_e32 v30, v30, v55
	v_mul_f32_e32 v31, v31, v55
	s_branch .LBB0_106

.LBB0_129:
	v_ashrrev_i32_e32 v0, 6, v38
	v_lshrrev_b32_e32 v1, 28, v0
	v_add_u32_e32 v1, v0, v1
	v_and_b32_e32 v2, -16, v1
	v_sub_u32_e32 v0, v0, v2
	v_lshlrev_b32_e32 v1, 2, v1
	v_and_b32_e32 v2, 56, v37
	v_lshlrev_b32_e32 v39, 5, v0
	v_and_or_b32 v32, v1, s18, v2
	v_lshlrev_b32_e32 v2, 6, v0
	v_lshrrev_b32_e32 v4, 3, v38
	v_and_b32_e32 v1, 0xffffff00, v39
	v_and_b32_e32 v2, 0xc0, v2
	v_lshlrev_b32_e32 v0, 3, v0
	v_and_b32_e32 v4, 4, v4
	v_and_b32_e32 v0, 32, v0
	v_and_b32_e32 v3, 24, v38
	v_or3_b32 v1, v1, v4, v2
	v_or3_b32 v0, v1, v0, v3
	v_readlane_b32 s36, v246, 38
	v_ashrrev_i32_e32 v1, 31, v0
	v_readlane_b32 s37, v246, 39
	v_ashrrev_i32_e32 v33, 31, v32
	v_readlane_b32 s38, v246, 40
	v_lshl_add_u64 v[28:29], v[0:1], 2, s[36:37]
	v_lshlrev_b64 v[0:1], 11, v[32:33]
	v_lshl_add_u64 v[0:1], v[28:29], 0, v[0:1]
	global_load_dwordx4 v[0:3], v[0:1], off nt
	v_readlane_b32 s39, v246, 41
	v_readlane_b32 s40, v246, 42
	v_readlane_b32 s41, v246, 43
	v_readlane_b32 s42, v246, 44
	v_readlane_b32 s43, v246, 45
	v_readlane_b32 s44, v246, 46
	v_readlane_b32 s45, v246, 47
	v_readlane_b32 s46, v246, 48
	v_readlane_b32 s47, v246, 49
	v_readlane_b32 s48, v246, 50
	v_readlane_b32 s49, v246, 51
	v_readlane_b32 s50, v246, 52
	v_readlane_b32 s51, v246, 53
	v_readlane_b32 s36, v246, 22
	v_readlane_b32 s48, v246, 34
	v_readlane_b32 s49, v246, 35
	v_readlane_b32 s37, v246, 23
	v_lshl_add_u64 v[34:35], v[32:33], 2, s[48:49]
	v_readlane_b32 s38, v246, 24
	v_readlane_b32 s39, v246, 25
	v_readlane_b32 s40, v246, 26
	v_readlane_b32 s41, v246, 27
	v_readlane_b32 s42, v246, 28
	v_readlane_b32 s43, v246, 29
	v_readlane_b32 s44, v246, 30
	v_readlane_b32 s45, v246, 31
	v_readlane_b32 s46, v246, 32
	v_readlane_b32 s47, v246, 33
	v_readlane_b32 s50, v246, 36
	v_readlane_b32 s51, v246, 37
	v_or_b32_e32 v4, 1, v32
	v_ashrrev_i32_e32 v5, 31, v4
	v_lshlrev_b64 v[4:5], 11, v[4:5]
	v_lshl_add_u64 v[4:5], v[28:29], 0, v[4:5]
	global_load_dwordx4 v[4:7], v[4:5], off nt
	v_or_b32_e32 v8, 2, v32
	v_ashrrev_i32_e32 v9, 31, v8
	v_lshlrev_b64 v[8:9], 11, v[8:9]
	v_lshl_add_u64 v[8:9], v[28:29], 0, v[8:9]
	global_load_dwordx4 v[8:11], v[8:9], off nt
	v_or_b32_e32 v12, 3, v32
	v_ashrrev_i32_e32 v13, 31, v12
	v_lshlrev_b64 v[12:13], 11, v[12:13]
	v_lshl_add_u64 v[12:13], v[28:29], 0, v[12:13]
	global_load_dwordx4 v[12:15], v[12:13], off nt
	v_or_b32_e32 v16, 4, v32
	v_ashrrev_i32_e32 v17, 31, v16
	v_lshlrev_b64 v[16:17], 11, v[16:17]
	v_lshl_add_u64 v[16:17], v[28:29], 0, v[16:17]
	global_load_dwordx4 v[16:19], v[16:17], off nt
	s_waitcnt lgkmcnt(0)
	v_or_b32_e32 v20, 5, v32
	s_waitcnt lgkmcnt(0)
	v_ashrrev_i32_e32 v21, 31, v20
	v_lshlrev_b64 v[20:21], 11, v[20:21]
	v_lshl_add_u64 v[20:21], v[28:29], 0, v[20:21]
	global_load_dwordx4 v[20:23], v[20:21], off nt
	v_or_b32_e32 v24, 6, v32
	v_ashrrev_i32_e32 v25, 31, v24
	v_lshlrev_b64 v[24:25], 11, v[24:25]
	v_lshl_add_u64 v[24:25], v[28:29], 0, v[24:25]
	global_load_dwordx4 v[24:27], v[24:25], off nt
	v_or_b32_e32 v30, 7, v32
	v_ashrrev_i32_e32 v31, 31, v30
	v_lshlrev_b64 v[30:31], 11, v[30:31]
	v_lshl_add_u64 v[28:29], v[28:29], 0, v[30:31]
	global_load_dwordx4 v[28:31], v[28:29], off nt
	s_and_b64 vcc, exec, s[8:9]
	s_cbranch_vccnz .LBB0_128
	global_load_dwordx4 v[48:51], v[34:35], off
	global_load_dwordx4 v[52:55], v[34:35], off offset:16
	s_waitcnt vmcnt(0)
	v_mul_f32_e32 v0, v0, v48
	v_mul_f32_e32 v1, v1, v48
	v_mul_f32_e32 v2, v2, v48
	v_mul_f32_e32 v3, v3, v48
	v_mul_f32_e32 v4, v4, v49
	v_mul_f32_e32 v5, v5, v49
	v_mul_f32_e32 v6, v6, v49
	v_mul_f32_e32 v7, v7, v49
	v_mul_f32_e32 v8, v8, v50
	v_mul_f32_e32 v9, v9, v50
	v_mul_f32_e32 v10, v10, v50
	v_mul_f32_e32 v11, v11, v50
	v_mul_f32_e32 v12, v12, v51
	v_mul_f32_e32 v13, v13, v51
	v_mul_f32_e32 v14, v14, v51
	v_mul_f32_e32 v15, v15, v51
	v_mul_f32_e32 v16, v16, v52
	v_mul_f32_e32 v17, v17, v52
	v_mul_f32_e32 v18, v18, v52
	v_mul_f32_e32 v19, v19, v52
	v_mul_f32_e32 v20, v20, v53
	v_mul_f32_e32 v21, v21, v53
	v_mul_f32_e32 v22, v22, v53
	v_mul_f32_e32 v23, v23, v53
	v_mul_f32_e32 v24, v24, v54
	v_mul_f32_e32 v25, v25, v54
	v_mul_f32_e32 v26, v26, v54
	v_mul_f32_e32 v27, v27, v54
	v_mul_f32_e32 v28, v28, v55
	v_mul_f32_e32 v29, v29, v55
	v_mul_f32_e32 v30, v30, v55
	v_mul_f32_e32 v31, v31, v55
	s_branch .LBB0_128

.LBB0_148:
	v_ashrrev_i32_e32 v0, 6, v38
	v_lshrrev_b32_e32 v1, 27, v0
	v_add_u32_e32 v1, v0, v1
	v_and_b32_e32 v2, 0xffffffe0, v1
	v_sub_u32_e32 v0, v0, v2
	v_lshlrev_b32_e32 v1, 1, v1
	v_and_b32_e32 v2, 56, v37
	v_lshlrev_b32_e32 v39, 5, v0
	v_and_or_b32 v32, v1, s15, v2
	v_lshlrev_b32_e32 v2, 6, v0
	v_lshrrev_b32_e32 v4, 3, v38
	v_and_b32_e32 v1, 0xffffff00, v39
	v_and_b32_e32 v2, 0xc0, v2
	v_lshlrev_b32_e32 v0, 3, v0
	v_and_b32_e32 v4, 4, v4
	v_and_b32_e32 v0, 32, v0
	v_and_b32_e32 v3, 24, v38
	v_or3_b32 v1, v1, v4, v2
	v_or3_b32 v0, v1, v0, v3
	v_readlane_b32 s36, v246, 38
	v_ashrrev_i32_e32 v1, 31, v0
	v_readlane_b32 s38, v246, 40
	v_readlane_b32 s39, v246, 41
	v_ashrrev_i32_e32 v33, 31, v32
	v_readlane_b32 s37, v246, 39
	v_lshl_add_u64 v[28:29], v[0:1], 2, s[38:39]
	v_lshlrev_b64 v[0:1], 12, v[32:33]
	v_lshl_add_u64 v[0:1], v[28:29], 0, v[0:1]
	global_load_dwordx4 v[0:3], v[0:1], off nt
	v_readlane_b32 s40, v246, 42
	v_readlane_b32 s41, v246, 43
	v_readlane_b32 s42, v246, 44
	v_readlane_b32 s43, v246, 45
	v_readlane_b32 s44, v246, 46
	v_readlane_b32 s45, v246, 47
	v_readlane_b32 s46, v246, 48
	v_readlane_b32 s47, v246, 49
	v_readlane_b32 s48, v246, 50
	v_readlane_b32 s49, v246, 51
	v_readlane_b32 s50, v246, 52
	v_readlane_b32 s51, v246, 53
	v_readlane_b32 s36, v246, 22
	v_readlane_b32 s50, v246, 36
	v_readlane_b32 s51, v246, 37
	v_readlane_b32 s37, v246, 23
	v_lshl_add_u64 v[34:35], v[32:33], 2, s[50:51]
	v_readlane_b32 s38, v246, 24
	v_readlane_b32 s39, v246, 25
	v_readlane_b32 s40, v246, 26
	v_readlane_b32 s41, v246, 27
	v_readlane_b32 s42, v246, 28
	v_readlane_b32 s43, v246, 29
	v_readlane_b32 s44, v246, 30
	v_readlane_b32 s45, v246, 31
	v_readlane_b32 s46, v246, 32
	v_readlane_b32 s47, v246, 33
	v_readlane_b32 s48, v246, 34
	v_readlane_b32 s49, v246, 35
	v_or_b32_e32 v4, 1, v32
	v_ashrrev_i32_e32 v5, 31, v4
	v_lshlrev_b64 v[4:5], 12, v[4:5]
	v_lshl_add_u64 v[4:5], v[28:29], 0, v[4:5]
	global_load_dwordx4 v[4:7], v[4:5], off nt
	v_or_b32_e32 v8, 2, v32
	v_ashrrev_i32_e32 v9, 31, v8
	v_lshlrev_b64 v[8:9], 12, v[8:9]
	v_lshl_add_u64 v[8:9], v[28:29], 0, v[8:9]
	global_load_dwordx4 v[8:11], v[8:9], off nt
	v_or_b32_e32 v12, 3, v32
	v_ashrrev_i32_e32 v13, 31, v12
	v_lshlrev_b64 v[12:13], 12, v[12:13]
	v_lshl_add_u64 v[12:13], v[28:29], 0, v[12:13]
	global_load_dwordx4 v[12:15], v[12:13], off nt
	v_or_b32_e32 v16, 4, v32
	v_ashrrev_i32_e32 v17, 31, v16
	v_lshlrev_b64 v[16:17], 12, v[16:17]
	v_lshl_add_u64 v[16:17], v[28:29], 0, v[16:17]
	global_load_dwordx4 v[16:19], v[16:17], off nt
	s_waitcnt lgkmcnt(0)
	v_or_b32_e32 v20, 5, v32
	s_waitcnt lgkmcnt(0)
	v_ashrrev_i32_e32 v21, 31, v20
	v_lshlrev_b64 v[20:21], 12, v[20:21]
	v_lshl_add_u64 v[20:21], v[28:29], 0, v[20:21]
	global_load_dwordx4 v[20:23], v[20:21], off nt
	v_or_b32_e32 v24, 6, v32
	v_ashrrev_i32_e32 v25, 31, v24
	v_lshlrev_b64 v[24:25], 12, v[24:25]
	v_lshl_add_u64 v[24:25], v[28:29], 0, v[24:25]
	global_load_dwordx4 v[24:27], v[24:25], off nt
	v_or_b32_e32 v30, 7, v32
	v_ashrrev_i32_e32 v31, 31, v30
	v_lshlrev_b64 v[30:31], 12, v[30:31]
	v_lshl_add_u64 v[28:29], v[28:29], 0, v[30:31]
	global_load_dwordx4 v[28:31], v[28:29], off nt
	s_and_b64 vcc, exec, s[6:7]
	s_cbranch_vccnz .LBB0_147
	global_load_dwordx4 v[48:51], v[34:35], off
	global_load_dwordx4 v[52:55], v[34:35], off offset:16
	s_waitcnt vmcnt(0)
	v_mul_f32_e32 v0, v0, v48
	v_mul_f32_e32 v1, v1, v48
	v_mul_f32_e32 v2, v2, v48
	v_mul_f32_e32 v3, v3, v48
	v_mul_f32_e32 v4, v4, v49
	v_mul_f32_e32 v5, v5, v49
	v_mul_f32_e32 v6, v6, v49
	v_mul_f32_e32 v7, v7, v49
	v_mul_f32_e32 v8, v8, v50
	v_mul_f32_e32 v9, v9, v50
	v_mul_f32_e32 v10, v10, v50
	v_mul_f32_e32 v11, v11, v50
	v_mul_f32_e32 v12, v12, v51
	v_mul_f32_e32 v13, v13, v51
	v_mul_f32_e32 v14, v14, v51
	v_mul_f32_e32 v15, v15, v51
	v_mul_f32_e32 v16, v16, v52
	v_mul_f32_e32 v17, v17, v52
	v_mul_f32_e32 v18, v18, v52
	v_mul_f32_e32 v19, v19, v52
	v_mul_f32_e32 v20, v20, v53
	v_mul_f32_e32 v21, v21, v53
	v_mul_f32_e32 v22, v22, v53
	v_mul_f32_e32 v23, v23, v53
	v_mul_f32_e32 v24, v24, v54
	v_mul_f32_e32 v25, v25, v54
	v_mul_f32_e32 v26, v26, v54
	v_mul_f32_e32 v27, v27, v54
	v_mul_f32_e32 v28, v28, v55
	v_mul_f32_e32 v29, v29, v55
	v_mul_f32_e32 v30, v30, v55
	v_mul_f32_e32 v31, v31, v55
	s_branch .LBB0_147

.LBB0_170:
	v_ashrrev_i32_e32 v0, 6, v38
	v_mul_hi_i32 v1, v0, s13
	v_lshrrev_b32_e32 v2, 31, v1
	v_ashrrev_i32_e32 v1, 5, v1
	v_add_u32_e32 v1, v1, v2
	v_mul_lo_u32 v2, v1, s14
	v_sub_u32_e32 v0, v0, v2
	v_and_b32_e32 v2, 56, v37
	v_lshlrev_b32_e32 v39, 5, v0
	v_lshl_or_b32 v32, v1, 6, v2
	v_bfe_i32 v1, v0, 2, 1
	v_lshlrev_b32_e32 v0, 4, v0
	v_and_b32_e32 v1, 0xb00, v1
	v_and_b32_e32 v0, 0xffffff80, v0
	v_add_u32_e32 v0, v1, v0
	v_lshrrev_b32_e32 v2, 3, v38
	v_and_or_b32 v0, v39, s15, v0
	v_and_b32_e32 v1, 24, v38
	v_and_b32_e32 v2, 4, v2
	v_or3_b32 v0, v0, v1, v2
	v_readlane_b32 s36, v246, 38
	v_ashrrev_i32_e32 v1, 31, v0
	v_readlane_b32 s48, v246, 50
	v_readlane_b32 s49, v246, 51
	v_readlane_b32 s46, v246, 48
	v_readlane_b32 s47, v246, 49
	v_lshl_add_u64 v[28:29], v[0:1], 2, s[48:49]
	v_mad_i64_i32 v[0:1], s[24:25], v32, s17, v[28:29]
	global_load_dwordx4 v[0:3], v[0:1], off nt
	v_ashrrev_i32_e32 v33, 31, v32
	v_lshl_add_u64 v[34:35], v[32:33], 2, s[46:47]
	v_readlane_b32 s37, v246, 39
	v_readlane_b32 s38, v246, 40
	v_readlane_b32 s39, v246, 41
	v_readlane_b32 s40, v246, 42
	v_readlane_b32 s41, v246, 43
	v_readlane_b32 s42, v246, 44
	v_readlane_b32 s43, v246, 45
	v_readlane_b32 s44, v246, 46
	v_readlane_b32 s45, v246, 47
	v_readlane_b32 s50, v246, 52
	v_readlane_b32 s51, v246, 53
	v_or_b32_e32 v4, 1, v32
	v_mad_i64_i32 v[4:5], s[24:25], v4, s17, v[28:29]
	global_load_dwordx4 v[4:7], v[4:5], off nt
	v_or_b32_e32 v8, 2, v32
	v_mad_i64_i32 v[8:9], s[24:25], v8, s17, v[28:29]
	global_load_dwordx4 v[8:11], v[8:9], off nt
	v_or_b32_e32 v12, 3, v32
	v_mad_i64_i32 v[12:13], s[24:25], v12, s17, v[28:29]
	global_load_dwordx4 v[12:15], v[12:13], off nt
	v_or_b32_e32 v16, 4, v32
	v_mad_i64_i32 v[16:17], s[24:25], v16, s17, v[28:29]
	global_load_dwordx4 v[16:19], v[16:17], off nt
	s_waitcnt lgkmcnt(0)
	v_or_b32_e32 v20, 5, v32
	s_waitcnt lgkmcnt(0)
	v_mad_i64_i32 v[20:21], s[24:25], v20, s17, v[28:29]
	global_load_dwordx4 v[20:23], v[20:21], off nt
	v_or_b32_e32 v24, 6, v32
	v_mad_i64_i32 v[24:25], s[24:25], v24, s17, v[28:29]
	global_load_dwordx4 v[24:27], v[24:25], off nt
	v_or_b32_e32 v30, 7, v32
	v_mad_i64_i32 v[28:29], s[24:25], v30, s17, v[28:29]
	global_load_dwordx4 v[28:31], v[28:29], off nt
	s_and_b64 vcc, exec, s[0:1]
	s_cbranch_vccnz .LBB0_169
	global_load_dwordx4 v[48:51], v[34:35], off
	global_load_dwordx4 v[52:55], v[34:35], off offset:16
	s_waitcnt vmcnt(0)
	v_mul_f32_e32 v0, v0, v48
	v_mul_f32_e32 v1, v1, v48
	v_mul_f32_e32 v2, v2, v48
	v_mul_f32_e32 v3, v3, v48
	v_mul_f32_e32 v4, v4, v49
	v_mul_f32_e32 v5, v5, v49
	v_mul_f32_e32 v6, v6, v49
	v_mul_f32_e32 v7, v7, v49
	v_mul_f32_e32 v8, v8, v50
	v_mul_f32_e32 v9, v9, v50
	v_mul_f32_e32 v10, v10, v50
	v_mul_f32_e32 v11, v11, v50
	v_mul_f32_e32 v12, v12, v51
	v_mul_f32_e32 v13, v13, v51
	v_mul_f32_e32 v14, v14, v51
	v_mul_f32_e32 v15, v15, v51
	v_mul_f32_e32 v16, v16, v52
	v_mul_f32_e32 v17, v17, v52
	v_mul_f32_e32 v18, v18, v52
	v_mul_f32_e32 v19, v19, v52
	v_mul_f32_e32 v20, v20, v53
	v_mul_f32_e32 v21, v21, v53
	v_mul_f32_e32 v22, v22, v53
	v_mul_f32_e32 v23, v23, v53
	v_mul_f32_e32 v24, v24, v54
	v_mul_f32_e32 v25, v25, v54
	v_mul_f32_e32 v26, v26, v54
	v_mul_f32_e32 v27, v27, v54
	v_mul_f32_e32 v28, v28, v55
	v_mul_f32_e32 v29, v29, v55
	v_mul_f32_e32 v30, v30, v55
	v_mul_f32_e32 v31, v31, v55
	s_branch .LBB0_169
